# hoist the loop-invariant forget-bias load out of the forget-logit row loop; batch the four gate-vector loads of the down-projection epilogue
# baseline (speedup 1.0000x reference)
;     __device__ __forceinline__ void fused(f32x4 (&acc)[2][2][4][2], const Unit& u, int wr, int wc, int fr, int fq, PG8_LAS unsigned char* lds, int wid, int lane) const {
;         const int row0 = u.pm * BM + wr * 64 + fr, col0 = u.pn * BM + wc * 32 + 4 * fq; const int bo = (u.pm >= 32 ? 9216 : 0); const float* gp = gate + bo + col0;
;         f32x4 gv[2][2];
; #pragma unroll
;         for (int bj = 0; bj < 2; ++bj)
; #pragma unroll
;             for (int n = 0; n < 2; ++n) gv[bj][n] = *(const f32x4*)(gp + bj * HALF + n * 16) * coef;
; #pragma unroll
;         for (int ai = 0; ai < 2; ++ai)
; #pragma unroll
;             for (int m = 0; m < 4; ++m) { const size_t off = (size_t)(row0 + ai * HALF + m * 16) * 1024 + col0;
; #pragma unroll
;                 for (int bj = 0; bj < 2; ++bj)
; #pragma unroll
;                     for (int n = 0; n < 2; ++n) { const f32x4 bs = *(const f32x4*)(base + off + bj * HALF + n * 16); acc[ai][bj][m][n] = bs + gv[bj][n] * acc[ai][bj][m][n]; *(f32x4*)(out + off + bj * HALF + n * 16) = acc[ai][bj][m][n]; }
;                 if (m & 1) asm volatile("" ::: "memory"); }
.LBB0_387:
	v_readlane_b32 s0, v255, 17
	v_readlane_b32 s1, v255, 18
	s_and_b64 s[4:5], s[0:1], s[12:13]
	v_readlane_b32 s0, v255, 13
	s_or_b32 s0, s3, s0
	s_cmp_eq_u32 s0, 0
	v_readlane_b32 s0, v255, 21
	v_readlane_b32 s1, v255, 22
	s_cselect_b32 s7, s23, s21
	s_cselect_b32 s6, s22, s20
	s_lshl_b64 s[0:1], s[0:1], 2
	s_add_u32 s8, s14, s0
	s_addc_u32 s9, s15, s1
	s_and_b64 s[0:1], s[12:13], exec
	s_movk_i32 s0, 0x2000
	s_cselect_b32 s0, 0x8000, s0
	s_add_u32 s8, s8, s0
	s_addc_u32 s9, s9, 0
	s_lshl_b32 s1, s38, 5
	s_lshl_b32 s0, s37, 8
	s_lshl_b32 s23, s18, 8
	s_add_i32 s22, s0, s49
	s_or_b32 s1, s23, s1
	v_lshrrev_b32_e32 v0, 2, v153
	s_cmp_gt_i32 s37, 31
	v_and_or_b32 v140, v0, 12, s1
	s_cselect_b32 s1, 0x2400, 0
	s_lshl_b32 s1, s1, 2
	s_add_u32 s8, s8, s1
	s_addc_u32 s9, s9, 0
	v_ashrrev_i32_e32 v141, 31, v140
	v_lshl_add_u64 v[150:151], v[140:141], 2, s[8:9]
	s_barrier
	global_load_dwordx4 v[130:133], v[150:151], off
	global_load_dwordx4 v[154:157], v[150:151], off offset:576
	global_load_dwordx4 v[186:189], v[150:151], off offset:64
	global_load_dwordx4 v[190:193], v[150:151], off offset:512
	s_mov_b64 s[8:9], 0x80000
	s_and_b64 vcc, exec, s[4:5]
	s_movk_i32 s58, 0x7fff
	s_mov_b32 s59, 0xffff0000
	s_mov_b64 s[60:61], 0x1000
	s_waitcnt vmcnt(0)
	v_pk_mul_f32 v[144:145], v[132:133], 0.5 op_sel_hi:[1,0]
	v_pk_mul_f32 v[146:147], v[130:131], 0.5 op_sel_hi:[1,0]
	s_nop 0
	s_waitcnt vmcnt(0)
	v_pk_mul_f32 v[138:139], v[188:189], 0.5 op_sel_hi:[1,0]
	v_pk_mul_f32 v[142:143], v[186:187], 0.5 op_sel_hi:[1,0]
	s_nop 0
	v_or_b32_e32 v150, s22, v148
	v_ashrrev_i32_e32 v151, 31, v150
	v_lshlrev_b64 v[148:149], 10, v[150:151]
	v_lshl_add_u64 v[148:149], v[148:149], 0, v[140:141]
	v_lshlrev_b64 v[148:149], 2, v[148:149]
	v_lshl_add_u64 v[158:159], s[6:7], 0, v[148:149]
	v_lshl_add_u64 v[160:161], s[20:21], 0, v[148:149]
	s_waitcnt vmcnt(0)
	v_pk_mul_f32 v[134:135], v[192:193], 0.5 op_sel_hi:[1,0]
	v_pk_mul_f32 v[136:137], v[190:191], 0.5 op_sel_hi:[1,0]
	v_pk_mul_f32 v[130:131], v[156:157], 0.5 op_sel_hi:[1,0]
	v_pk_mul_f32 v[132:133], v[154:155], 0.5 op_sel_hi:[1,0]
	global_load_dwordx4 v[170:173], v[158:159], off nt
	global_load_dwordx4 v[174:177], v[158:159], off offset:64 nt
	global_load_dwordx4 v[178:181], v[158:159], off offset:512 nt
	global_load_dwordx4 v[182:185], v[158:159], off offset:576 nt
	s_waitcnt vmcnt(3)
	v_pk_fma_f32 v[116:117], v[116:117], v[144:145], v[172:173]
	v_pk_fma_f32 v[114:115], v[114:115], v[146:147], v[170:171]
	global_store_dwordx4 v[160:161], v[114:117], off nt
	s_waitcnt vmcnt(3)
	v_pk_fma_f32 v[84:85], v[84:85], v[138:139], v[176:177]
	v_pk_fma_f32 v[82:83], v[82:83], v[142:143], v[174:175]
	global_store_dwordx4 v[160:161], v[82:85], off offset:64 nt
	s_waitcnt vmcnt(3)
	v_pk_fma_f32 v[28:29], v[28:29], v[134:135], v[180:181]
	v_pk_fma_f32 v[26:27], v[26:27], v[136:137], v[178:179]
	global_store_dwordx4 v[160:161], v[26:29], off offset:512 nt
	s_waitcnt vmcnt(3)
	v_pk_fma_f32 v[2:3], v[2:3], v[132:133], v[182:183]
	v_or_b32_e32 v154, 16, v150
	v_ashrrev_i32_e32 v155, 31, v154
	v_lshlrev_b64 v[154:155], 10, v[154:155]
	v_lshl_add_u64 v[154:155], v[154:155], 0, v[140:141]
	v_pk_fma_f32 v[4:5], v[4:5], v[130:131], v[184:185]
	v_lshlrev_b64 v[158:159], 2, v[154:155]
	global_store_dwordx4 v[160:161], v[2:5], off offset:576 nt
	v_lshl_add_u64 v[160:161], s[6:7], 0, v[158:159]
	global_load_dwordx4 v[170:173], v[160:161], off nt
	global_load_dwordx4 v[174:177], v[160:161], off offset:64 nt
	global_load_dwordx4 v[178:181], v[160:161], off offset:512 nt
	global_load_dwordx4 v[182:185], v[160:161], off offset:576 nt
	v_lshl_add_u64 v[158:159], s[20:21], 0, v[158:159]
	s_waitcnt vmcnt(3)
	v_pk_fma_f32 v[124:125], v[124:125], v[144:145], v[172:173]
	v_pk_fma_f32 v[122:123], v[122:123], v[146:147], v[170:171]
	global_store_dwordx4 v[158:159], v[122:125], off nt
	s_waitcnt vmcnt(3)
	v_pk_fma_f32 v[96:97], v[96:97], v[138:139], v[176:177]
	v_pk_fma_f32 v[94:95], v[94:95], v[142:143], v[174:175]
	global_store_dwordx4 v[158:159], v[94:97], off offset:64 nt
	s_waitcnt vmcnt(3)
	v_pk_fma_f32 v[36:37], v[36:37], v[134:135], v[180:181]
	v_pk_fma_f32 v[34:35], v[34:35], v[136:137], v[178:179]
	global_store_dwordx4 v[158:159], v[34:37], off offset:512 nt
	s_waitcnt vmcnt(3)
	v_pk_fma_f32 v[6:7], v[6:7], v[132:133], v[182:183]
	v_or_b32_e32 v154, 32, v150
	v_ashrrev_i32_e32 v155, 31, v154
	v_lshlrev_b64 v[154:155], 10, v[154:155]
	v_pk_fma_f32 v[8:9], v[8:9], v[130:131], v[184:185]
	v_lshl_add_u64 v[154:155], v[154:155], 0, v[140:141]
	global_store_dwordx4 v[158:159], v[6:9], off offset:576 nt
	v_lshlrev_b64 v[158:159], 2, v[154:155]
	v_lshl_add_u64 v[160:161], s[6:7], 0, v[158:159]
	global_load_dwordx4 v[170:173], v[160:161], off nt
	global_load_dwordx4 v[174:177], v[160:161], off offset:64 nt
	global_load_dwordx4 v[178:181], v[160:161], off offset:512 nt
	global_load_dwordx4 v[182:185], v[160:161], off offset:576 nt
	v_lshl_add_u64 v[158:159], s[20:21], 0, v[158:159]
	v_or_b32_e32 v150, 48, v150
	v_ashrrev_i32_e32 v151, 31, v150
	v_lshlrev_b64 v[150:151], 10, v[150:151]
	v_lshl_add_u64 v[150:151], v[150:151], 0, v[140:141]
	v_lshlrev_b64 v[150:151], 2, v[150:151]
	s_waitcnt vmcnt(3)
	v_pk_fma_f32 v[128:129], v[128:129], v[144:145], v[172:173]
	v_pk_fma_f32 v[126:127], v[126:127], v[146:147], v[170:171]
	global_store_dwordx4 v[158:159], v[126:129], off nt
	s_waitcnt vmcnt(3)
	v_pk_fma_f32 v[108:109], v[108:109], v[138:139], v[176:177]
	v_pk_fma_f32 v[106:107], v[106:107], v[142:143], v[174:175]
	global_store_dwordx4 v[158:159], v[106:109], off offset:64 nt
	s_waitcnt vmcnt(3)
;     __device__ __forceinline__ void fused(f32x4 (&acc)[2][2][4][2], const Unit& u, int wr, int wc, int fr, int fq, PG8_LAS unsigned char* lds, int wid, int lane) const {
;     ...
;             for (int m = 0; m < 4; ++m) { const size_t off = (size_t)(row0 + ai * HALF + m * 16) * 1024 + col0;
; #pragma unroll
;                 for (int bj = 0; bj < 2; ++bj)
; #pragma unroll
;                     for (int n = 0; n < 2; ++n) { const f32x4 bs = *(const f32x4*)(base + off + bj * HALF + n * 16); acc[ai][bj][m][n] = bs + gv[bj][n] * acc[ai][bj][m][n]; *(f32x4*)(out + off + bj * HALF + n * 16) = acc[ai][bj][m][n]; }
;                 if (m & 1) asm volatile("" ::: "memory"); }
	v_pk_fma_f32 v[44:45], v[44:45], v[134:135], v[180:181]
	v_pk_fma_f32 v[42:43], v[42:43], v[136:137], v[178:179]
	global_store_dwordx4 v[158:159], v[42:45], off offset:512 nt
	s_waitcnt vmcnt(3)
	v_pk_fma_f32 v[12:13], v[12:13], v[130:131], v[184:185]
	v_pk_fma_f32 v[10:11], v[10:11], v[132:133], v[182:183]
	global_store_dwordx4 v[158:159], v[10:13], off offset:576 nt
	v_lshl_add_u64 v[158:159], s[6:7], 0, v[150:151]
	global_load_dwordx4 v[170:173], v[158:159], off nt
	global_load_dwordx4 v[174:177], v[158:159], off offset:64 nt
	global_load_dwordx4 v[178:181], v[158:159], off offset:512 nt
	global_load_dwordx4 v[182:185], v[158:159], off offset:576 nt
	v_lshl_add_u64 v[150:151], s[20:21], 0, v[150:151]
	s_waitcnt vmcnt(3)
	v_pk_fma_f32 v[120:121], v[120:121], v[144:145], v[172:173]
	v_pk_fma_f32 v[118:119], v[118:119], v[146:147], v[170:171]
	global_store_dwordx4 v[150:151], v[118:121], off nt
	s_waitcnt vmcnt(3)
	v_pk_fma_f32 v[112:113], v[112:113], v[138:139], v[176:177]
	v_pk_fma_f32 v[110:111], v[110:111], v[142:143], v[174:175]
	global_store_dwordx4 v[150:151], v[110:113], off offset:64 nt
	s_waitcnt vmcnt(3)
	v_pk_fma_f32 v[48:49], v[48:49], v[134:135], v[180:181]
	v_pk_fma_f32 v[46:47], v[46:47], v[136:137], v[178:179]
	global_store_dwordx4 v[150:151], v[46:49], off offset:512 nt
	s_waitcnt vmcnt(3)
	v_pk_fma_f32 v[16:17], v[16:17], v[130:131], v[184:185]
	v_pk_fma_f32 v[14:15], v[14:15], v[132:133], v[182:183]
	global_store_dwordx4 v[150:151], v[14:17], off offset:576 nt
	v_lshl_add_u64 v[150:151], v[148:149], 0, s[8:9]
	v_lshl_add_u64 v[158:159], s[6:7], 0, v[150:151]
	global_load_dwordx4 v[170:173], v[158:159], off nt
	global_load_dwordx4 v[174:177], v[158:159], off offset:64 nt
	global_load_dwordx4 v[178:181], v[158:159], off offset:512 nt
	global_load_dwordx4 v[182:185], v[158:159], off offset:576 nt
	v_lshl_add_u64 v[150:151], s[20:21], 0, v[150:151]
	s_mov_b64 s[8:9], 0x90000
	s_waitcnt vmcnt(3)
	v_pk_fma_f32 v[104:105], v[104:105], v[144:145], v[172:173]
	v_pk_fma_f32 v[102:103], v[102:103], v[146:147], v[170:171]
	global_store_dwordx4 v[150:151], v[102:105], off nt
	s_waitcnt vmcnt(3)
	v_pk_fma_f32 v[100:101], v[100:101], v[138:139], v[176:177]
	v_pk_fma_f32 v[98:99], v[98:99], v[142:143], v[174:175]
	global_store_dwordx4 v[150:151], v[98:101], off offset:64 nt
	s_waitcnt vmcnt(3)
	v_pk_fma_f32 v[56:57], v[56:57], v[134:135], v[180:181]
	v_pk_fma_f32 v[54:55], v[54:55], v[136:137], v[178:179]
	global_store_dwordx4 v[150:151], v[54:57], off offset:512 nt
	s_waitcnt vmcnt(3)
	v_pk_fma_f32 v[20:21], v[20:21], v[130:131], v[184:185]
	v_pk_fma_f32 v[18:19], v[18:19], v[132:133], v[182:183]
	global_store_dwordx4 v[150:151], v[18:21], off offset:576 nt
	v_lshl_add_u64 v[150:151], v[148:149], 0, s[8:9]
	v_lshl_add_u64 v[158:159], s[6:7], 0, v[150:151]
	global_load_dwordx4 v[170:173], v[158:159], off nt
	global_load_dwordx4 v[174:177], v[158:159], off offset:64 nt
	global_load_dwordx4 v[178:181], v[158:159], off offset:512 nt
	global_load_dwordx4 v[182:185], v[158:159], off offset:576 nt
	v_lshl_add_u64 v[150:151], s[20:21], 0, v[150:151]
	s_mov_b64 s[8:9], 0xa0000
	s_waitcnt vmcnt(3)
	v_pk_fma_f32 v[92:93], v[92:93], v[144:145], v[172:173]
	v_pk_fma_f32 v[90:91], v[90:91], v[146:147], v[170:171]
	global_store_dwordx4 v[150:151], v[90:93], off nt
	s_waitcnt vmcnt(3)
	v_pk_fma_f32 v[88:89], v[88:89], v[138:139], v[176:177]
	v_pk_fma_f32 v[86:87], v[86:87], v[142:143], v[174:175]
	global_store_dwordx4 v[150:151], v[86:89], off offset:64 nt
	s_waitcnt vmcnt(3)
	v_pk_fma_f32 v[60:61], v[60:61], v[134:135], v[180:181]
	v_pk_fma_f32 v[58:59], v[58:59], v[136:137], v[178:179]
	global_store_dwordx4 v[150:151], v[58:61], off offset:512 nt
	s_waitcnt vmcnt(3)
	v_pk_fma_f32 v[32:33], v[32:33], v[130:131], v[184:185]
	v_pk_fma_f32 v[30:31], v[30:31], v[132:133], v[182:183]
	global_store_dwordx4 v[150:151], v[30:33], off offset:576 nt
	v_lshl_add_u64 v[150:151], v[148:149], 0, s[8:9]
	v_lshl_add_u64 v[158:159], s[6:7], 0, v[150:151]
	global_load_dwordx4 v[170:173], v[158:159], off nt
	global_load_dwordx4 v[174:177], v[158:159], off offset:64 nt
	global_load_dwordx4 v[178:181], v[158:159], off offset:512 nt
	global_load_dwordx4 v[182:185], v[158:159], off offset:576 nt
	v_lshl_add_u64 v[150:151], s[20:21], 0, v[150:151]
	s_mov_b64 s[8:9], 0xb0000
	s_waitcnt vmcnt(3)
	v_pk_fma_f32 v[80:81], v[80:81], v[144:145], v[172:173]
	v_pk_fma_f32 v[78:79], v[78:79], v[146:147], v[170:171]
	global_store_dwordx4 v[150:151], v[78:81], off nt
	s_waitcnt vmcnt(3)
	v_pk_fma_f32 v[76:77], v[76:77], v[138:139], v[176:177]
	v_pk_fma_f32 v[74:75], v[74:75], v[142:143], v[174:175]
	global_store_dwordx4 v[150:151], v[74:77], off offset:64 nt
	s_waitcnt vmcnt(3)
	v_pk_fma_f32 v[64:65], v[64:65], v[134:135], v[180:181]
	v_pk_fma_f32 v[62:63], v[62:63], v[136:137], v[178:179]
	global_store_dwordx4 v[150:151], v[62:65], off offset:512 nt
	s_waitcnt vmcnt(3)
	v_pk_fma_f32 v[40:41], v[40:41], v[130:131], v[184:185]
	v_pk_fma_f32 v[38:39], v[38:39], v[132:133], v[182:183]
	v_lshl_add_u64 v[154:155], v[148:149], 0, s[8:9]
	global_store_dwordx4 v[150:151], v[38:41], off offset:576 nt
	v_lshl_add_u64 v[156:157], s[6:7], 0, v[154:155]
	global_load_dwordx4 v[170:173], v[156:157], off nt
	global_load_dwordx4 v[174:177], v[156:157], off offset:64 nt
	global_load_dwordx4 v[178:181], v[156:157], off offset:512 nt
	global_load_dwordx4 v[182:185], v[156:157], off offset:576 nt
	s_waitcnt vmcnt(3)
	v_pk_fma_f32 v[72:73], v[72:73], v[144:145], v[172:173]
	v_pk_fma_f32 v[70:71], v[70:71], v[146:147], v[170:171]
	v_lshl_add_u64 v[148:149], s[20:21], 0, v[154:155]
	global_store_dwordx4 v[148:149], v[70:73], off nt
	s_waitcnt vmcnt(3)
	v_pk_fma_f32 v[68:69], v[68:69], v[138:139], v[176:177]
	v_pk_fma_f32 v[66:67], v[66:67], v[142:143], v[174:175]
	global_store_dwordx4 v[148:149], v[66:69], off offset:64 nt
	s_waitcnt vmcnt(3)
	v_pk_fma_f32 v[52:53], v[52:53], v[134:135], v[180:181]
	v_pk_fma_f32 v[50:51], v[50:51], v[136:137], v[178:179]
	global_store_dwordx4 v[148:149], v[50:53], off offset:512 nt
	s_waitcnt vmcnt(3)
	v_pk_fma_f32 v[24:25], v[24:25], v[130:131], v[184:185]
	v_pk_fma_f32 v[22:23], v[22:23], v[132:133], v[182:183]
	global_store_dwordx4 v[148:149], v[22:25], off offset:576 nt
	s_cbranch_vccnz .LBB0_425
;     __device__ __forceinline__ void fused(f32x4 (&acc)[2][2][4][2], const Unit& u, int wr, int wc, int fr, int fq, PG8_LAS unsigned char* lds, int wid, int lane) const {
;     ...
;         for (int ai = 0; ai < 2; ++ai)
; #pragma unroll
;             for (int m = 0; m < 4; ++m) { float q = 0.f;
; #pragma unroll
;                 for (int bj = 0; bj < 2; ++bj)
; #pragma unroll
;                     for (int n = 0; n < 2; ++n) { const f32x4 x = acc[ai][bj][m][n]; q += (x[0] * x[0] + x[1] * x[1]) + (x[2] * x[2] + x[3] * x[3]); }
;                 q += __shfl_xor(q, 16); q += __shfl_xor(q, 32);
;                 if (fq == 0) P[(ai * HALF + wr * 64 + m * 16 + fr) * 4 + wc] = q; }
	v_mul_f32_e32 v132, v115, v115
	v_mul_f32_e32 v133, v117, v117
	v_fmac_f32_e32 v132, v114, v114
	v_fmac_f32_e32 v133, v116, v116
	v_add_f32_e32 v132, v132, v133
	v_mul_f32_e32 v133, v83, v83
	v_mul_f32_e32 v134, v85, v85
	v_fmac_f32_e32 v133, v82, v82
	v_fmac_f32_e32 v134, v84, v84
	v_add_f32_e32 v133, v133, v134
	v_add_f32_e32 v132, v132, v133
	v_mul_f32_e32 v133, v27, v27
	v_mul_f32_e32 v134, v29, v29
	v_fmac_f32_e32 v133, v26, v26
	v_fmac_f32_e32 v134, v28, v28
	v_and_b32_e32 v131, 64, v240
	v_add_f32_e32 v133, v133, v134
	v_xor_b32_e32 v130, 16, v240
	v_add_u32_e32 v131, 64, v131
	v_add_f32_e32 v132, v132, v133
	v_mul_f32_e32 v133, v3, v3
	v_mul_f32_e32 v134, v5, v5
	v_cmp_lt_i32_e32 vcc, v130, v131
	v_fmac_f32_e32 v133, v2, v2
	v_fmac_f32_e32 v134, v4, v4
	v_cndmask_b32_e32 v130, v240, v130, vcc
	v_add_f32_e32 v133, v133, v134
	v_lshlrev_b32_e32 v130, 2, v130
	v_add_f32_e32 v133, v132, v133
	ds_bpermute_b32 v134, v130, v133
	v_xor_b32_e32 v132, 32, v240
	v_cmp_lt_i32_e32 vcc, v132, v131
	s_lshl_b32 s4, s38, 2
	v_and_b32_e32 v0, 63, v153
	v_cndmask_b32_e32 v131, v240, v132, vcc
	v_lshlrev_b32_e32 v132, 2, v131
	s_waitcnt lgkmcnt(0)
	v_add_f32_e32 v133, v133, v134
	ds_bpermute_b32 v134, v132, v133
	s_add_i32 s4, s4, 0
	v_cmp_gt_u32_e32 vcc, 16, v0
	v_lshl_add_u32 v131, v152, 4, s4
	s_and_saveexec_b64 s[4:5], vcc
	s_cbranch_execz .LBB0_390
	s_waitcnt lgkmcnt(0)
	v_add_f32_e32 v133, v133, v134
	ds_write_b32 v131, v133

; #define LAS __attribute__((address_space(3)))
; #define ARG_IN(i) argp(i)
; __device__ __forceinline__ void f_phase(int l, LAS unsigned char* lds, int vcu, int G, int tid, int wave, int lane) {
;     unsigned char* ws_ = ARG_WS; const bf16* XN = (const bf16*)(ws_ + WS_XN); const float* fb = ARG_IN(11) + l * 8;
;     LAS float* wfs = (LAS float*)lds; LAS float* lfs = (LAS float*)(lds + 32768);
;     { const float* WF = (const float*)(ws_ + WS_WF); for (int i = tid; i < 8192; i += 512) wfs[i] = WF[i]; __syncthreads(); }
;     for (int blk = vcu; blk < 256; blk += G) {
;         const int b = blk >> 7;
; #pragma unroll 2
;         for (int i = 0; i < 8; ++i) { const int rl = wave * 8 + i, row = blk * 64 + rl;
;             const v4u* xr = (const v4u*)(XN + (size_t)row * 1024) + lane;
;             const v4u a = xr[0], c = xr[64];
;             const f32x4 h0 = {__uint_as_float(a.x << 16), __uint_as_float(a.x & 0xffff0000u), __uint_as_float(a.y << 16), __uint_as_float(a.y & 0xffff0000u)};
;             const f32x4 h1 = {__uint_as_float(a.z << 16), __uint_as_float(a.z & 0xffff0000u), __uint_as_float(a.w << 16), __uint_as_float(a.w & 0xffff0000u)};
;             const f32x4 h2 = {__uint_as_float(c.x << 16), __uint_as_float(c.x & 0xffff0000u), __uint_as_float(c.y << 16), __uint_as_float(c.y & 0xffff0000u)};
;             const f32x4 h3 = {__uint_as_float(c.z << 16), __uint_as_float(c.z & 0xffff0000u), __uint_as_float(c.w << 16), __uint_as_float(c.w & 0xffff0000u)};
;             float p8[8];
; #pragma unroll
;             for (int hh = 0; hh < 8; ++hh) { const LAS f32x4* w = (const LAS f32x4*)(wfs + hh * 1024 + 8 * lane);
;                 const f32x4 w0 = w[0], w1 = w[1], w2 = w[128], w3 = w[129];
;                 float p = ((h0.x * w0.x + h0.y * w0.y) + (h0.z * w0.z + h0.w * w0.w)) + ((h1.x * w1.x + h1.y * w1.y) + (h1.z * w1.z + h1.w * w1.w))
;                         + ((h2.x * w2.x + h2.y * w2.y) + (h2.z * w2.z + h2.w * w2.w)) + ((h3.x * w3.x + h3.y * w3.y) + (h3.z * w3.z + h3.w * w3.w));
;                 p8[hh] = p; }
;             { const bool b32 = (lane & 32) != 0, b16 = (lane & 16) != 0, b8 = (lane & 8) != 0; float q4[4], q2[2], q1;
; #pragma unroll
;               for (int k = 0; k < 4; ++k) { const float mine = b32 ? p8[4 + k] : p8[k], send = b32 ? p8[k] : p8[4 + k]; q4[k] = mine + __shfl_xor(send, 32); }
; #pragma unroll
.LBB0_487:
	s_or_b64 exec, exec, s[6:7]
	v_mov_b32_e32 v0, 0xff
	v_cmp_gt_i32_e32 vcc, s30, v0
	s_and_b64 s[0:1], vcc, exec
	s_waitcnt lgkmcnt(0)
	s_barrier
	s_cbranch_scc1 .LBB0_498
	v_readlane_b32 s0, v255, 24
	v_readlane_b32 s1, v255, 25
	v_and_b32_e32 v2, 63, v10
	s_lshl_b64 s[0:1], s[0:1], 2
	s_add_u32 s0, s4, s0
	v_lshlrev_b32_e32 v0, 4, v2
	s_addc_u32 s1, s5, s1
	v_lshl_add_u64 v[4:5], s[10:11], 0, v[0:1]
	s_mov_b64 s[4:5], 0x3600000
	v_and_b32_e32 v0, 16, v10
	v_lshl_add_u64 v[12:13], v[4:5], 0, s[4:5]
	v_cmp_eq_u32_e64 s[4:5], 0, v0
	v_and_b32_e32 v0, 8, v10
	v_and_b32_e32 v3, 64, v240
	v_cmp_eq_u32_e64 s[6:7], 0, v0
	v_xor_b32_e32 v0, 32, v240
	v_add_u32_e32 v6, 64, v3
	v_cmp_lt_i32_e64 s[8:9], v0, v6
	s_add_u32 s31, s10, 0x100000
	s_addc_u32 s34, s11, 0
	v_cndmask_b32_e64 v0, v240, v0, s[8:9]
	v_lshlrev_b32_e32 v20, 2, v0
	v_xor_b32_e32 v0, 16, v240
	v_cmp_lt_i32_e64 s[8:9], v0, v6
	s_add_u32 s35, s10, 0x50000
	s_addc_u32 s36, s11, 0
	v_cndmask_b32_e64 v0, v240, v0, s[8:9]
	v_lshlrev_b32_e32 v21, 2, v0
	v_xor_b32_e32 v0, 8, v240
	v_cmp_lt_i32_e64 s[8:9], v0, v6
	v_lshlrev_b32_e32 v11, 5, v2
	v_cmp_gt_u32_e32 vcc, 32, v2
	v_cndmask_b32_e64 v0, v240, v0, s[8:9]
	v_lshlrev_b32_e32 v22, 2, v0
	v_xor_b32_e32 v0, 4, v240
	v_cmp_lt_i32_e64 s[8:9], v0, v6
	v_cmp_eq_u32_e64 s[10:11], 63, v2
	s_lshl_b32 s38, s41, 6
	v_cndmask_b32_e64 v0, v240, v0, s[8:9]
	v_lshlrev_b32_e32 v23, 2, v0
	v_xor_b32_e32 v0, 2, v240
	v_cmp_lt_i32_e64 s[8:9], v0, v6
	v_lshlrev_b32_e32 v32, 2, v2
	s_nop 0
	v_cndmask_b32_e64 v0, v240, v0, s[8:9]
	v_lshlrev_b32_e32 v24, 2, v0
	v_xor_b32_e32 v0, 1, v240
	v_cmp_lt_i32_e64 s[8:9], v0, v6
	v_add_u32_e32 v6, -1, v240
	v_cmp_lt_i32_e64 s[12:13], v6, v3
	v_cndmask_b32_e64 v0, v240, v0, s[8:9]
	v_lshlrev_b32_e32 v25, 2, v0
	v_cndmask_b32_e64 v6, v6, v240, s[12:13]
	v_lshlrev_b32_e32 v26, 2, v6
	v_add_u32_e32 v6, -2, v240
	v_cmp_lt_i32_e64 s[14:15], v6, v3
	v_and_b32_e32 v0, 7, v10
	v_cmp_eq_u32_e64 s[8:9], 0, v0
	v_cndmask_b32_e64 v6, v6, v240, s[14:15]
	v_lshlrev_b32_e32 v27, 2, v6
	v_add_u32_e32 v6, -4, v240
	v_cmp_lt_i32_e64 s[16:17], v6, v3
	v_lshrrev_b32_e32 v0, 1, v10
	v_and_b32_e32 v0, 28, v0
	v_cndmask_b32_e64 v6, v6, v240, s[16:17]
	v_lshlrev_b32_e32 v28, 2, v6
	v_add_u32_e32 v6, -8, v240
	v_cmp_lt_i32_e64 s[18:19], v6, v3
	v_lshl_add_u64 v[14:15], s[0:1], 0, v[0:1]
	global_load_dword v100, v[14:15], off
	v_readlane_b32 s0, v255, 7
	v_cndmask_b32_e64 v6, v6, v240, s[18:19]
	v_lshlrev_b32_e32 v29, 2, v6
	v_add_u32_e32 v6, -16, v240
	v_cmp_lt_i32_e64 s[20:21], v6, v3
	v_add_u32_e32 v0, s0, v0
	v_readlane_b32 s0, v255, 9
	v_cndmask_b32_e64 v6, v6, v240, s[20:21]
	v_lshlrev_b32_e32 v30, 2, v6
	v_subrev_u32_e32 v6, 32, v240
	v_cmp_lt_i32_e64 s[22:23], v6, v3
	v_cmp_eq_u32_e64 s[12:13], 0, v2
	v_cmp_gt_u32_e64 s[14:15], 2, v2
	v_cndmask_b32_e64 v3, v6, v240, s[22:23]
	s_lshl_b32 s22, s30, 6
	s_add_i32 s37, s0, s22
	s_mov_b64 s[0:1], 0x3600400
	v_lshl_add_u64 v[16:17], v[4:5], 0, s[0:1]
	v_readlane_b32 s0, v255, 8
	v_cmp_gt_u32_e64 s[16:17], 4, v2
	v_cmp_gt_u32_e64 s[18:19], 8, v2
	v_cmp_gt_u32_e64 s[20:21], 16, v2
	v_lshlrev_b32_e32 v31, 2, v3
	s_add_i32 s24, s0, s22
	s_branch .LBB0_490

; #define LAS __attribute__((address_space(3)))
; __device__ __forceinline__ void f_phase(int l, LAS unsigned char* lds, int vcu, int G, int tid, int wave, int lane) {
;     ...
;         for (int i = 0; i < 8; ++i) { const int rl = wave * 8 + i, row = blk * 64 + rl;
;             const v4u* xr = (const v4u*)(XN + (size_t)row * 1024) + lane;
;             const v4u a = xr[0], c = xr[64];
;             const f32x4 h0 = {__uint_as_float(a.x << 16), __uint_as_float(a.x & 0xffff0000u), __uint_as_float(a.y << 16), __uint_as_float(a.y & 0xffff0000u)};
;             const f32x4 h1 = {__uint_as_float(a.z << 16), __uint_as_float(a.z & 0xffff0000u), __uint_as_float(a.w << 16), __uint_as_float(a.w & 0xffff0000u)};
;             const f32x4 h2 = {__uint_as_float(c.x << 16), __uint_as_float(c.x & 0xffff0000u), __uint_as_float(c.y << 16), __uint_as_float(c.y & 0xffff0000u)};
;             const f32x4 h3 = {__uint_as_float(c.z << 16), __uint_as_float(c.z & 0xffff0000u), __uint_as_float(c.w << 16), __uint_as_float(c.w & 0xffff0000u)};
;             float p8[8];
; #pragma unroll
;             for (int hh = 0; hh < 8; ++hh) { const LAS f32x4* w = (const LAS f32x4*)(wfs + hh * 1024 + 8 * lane);
;                 const f32x4 w0 = w[0], w1 = w[1], w2 = w[128], w3 = w[129];
;                 float p = ((h0.x * w0.x + h0.y * w0.y) + (h0.z * w0.z + h0.w * w0.w)) + ((h1.x * w1.x + h1.y * w1.y) + (h1.z * w1.z + h1.w * w1.w))
;                         + ((h2.x * w2.x + h2.y * w2.y) + (h2.z * w2.z + h2.w * w2.w)) + ((h3.x * w3.x + h3.y * w3.y) + (h3.z * w3.z + h3.w * w3.w));
;                 p8[hh] = p; }
.LBB0_492:
	s_waitcnt lgkmcnt(0)
	global_load_dwordx4 v[2:5], v[18:19], off offset:-1024
	global_load_dwordx4 v[6:9], v[18:19], off
	v_add_u32_e32 v34, 0, v11
	s_waitcnt vmcnt(1)
	v_lshlrev_b32_e32 v46, 16, v2
	v_and_b32_e32 v49, 0xffff0000, v2
	v_lshlrev_b32_e32 v44, 16, v3
	v_and_b32_e32 v48, 0xffff0000, v3
	v_lshlrev_b32_e32 v43, 16, v4
	v_and_b32_e32 v47, 0xffff0000, v4
	v_lshlrev_b32_e32 v41, 16, v5
	v_and_b32_e32 v45, 0xffff0000, v5
	s_waitcnt vmcnt(0)
	v_lshlrev_b32_e32 v39, 16, v6
	v_and_b32_e32 v42, 0xffff0000, v6
	v_lshlrev_b32_e32 v37, 16, v7
	v_and_b32_e32 v40, 0xffff0000, v7
	v_lshlrev_b32_e32 v33, 16, v8
	v_and_b32_e32 v38, 0xffff0000, v8
	v_lshlrev_b32_e32 v35, 16, v9
	v_and_b32_e32 v36, 0xffff0000, v9
	ds_read_b128 v[2:5], v34
	ds_read_b128 v[6:9], v34 offset:16
	ds_read_b128 v[50:53], v34 offset:2048
	ds_read_b128 v[54:57], v34 offset:2064
	s_waitcnt lgkmcnt(3)
	v_mul_f32_e32 v3, v3, v49
	v_fmac_f32_e32 v3, v2, v46
	v_mul_f32_e32 v2, v5, v48
	v_fmac_f32_e32 v2, v4, v44
	v_add_f32_e32 v2, v3, v2
	s_waitcnt lgkmcnt(2)
	v_mul_f32_e32 v3, v7, v47
	v_mul_f32_e32 v4, v9, v45
	v_fmac_f32_e32 v3, v6, v43
	v_fmac_f32_e32 v4, v8, v41
	v_add_f32_e32 v3, v3, v4
	v_add_f32_e32 v2, v2, v3
	s_waitcnt lgkmcnt(1)
	v_mul_f32_e32 v3, v51, v42
	v_mul_f32_e32 v4, v53, v40
	v_fmac_f32_e32 v3, v50, v39
	v_fmac_f32_e32 v4, v52, v37
	v_add_f32_e32 v3, v3, v4
	v_add_f32_e32 v2, v2, v3
	s_waitcnt lgkmcnt(0)
	v_mul_f32_e32 v3, v55, v38
	v_mul_f32_e32 v4, v57, v36
	v_fmac_f32_e32 v3, v54, v33
	v_fmac_f32_e32 v4, v56, v35
	v_add_f32_e32 v3, v3, v4
	v_add_f32_e32 v50, v2, v3
	ds_read_b128 v[2:5], v34 offset:4096
	ds_read_b128 v[6:9], v34 offset:4112
	ds_read_b128 v[52:55], v34 offset:6144
	ds_read_b128 v[56:59], v34 offset:6160
	s_waitcnt lgkmcnt(3)
	v_mul_f32_e32 v3, v3, v49
	v_fmac_f32_e32 v3, v2, v46
	v_mul_f32_e32 v2, v5, v48
	v_fmac_f32_e32 v2, v4, v44
	v_add_f32_e32 v2, v3, v2
	s_waitcnt lgkmcnt(2)
	v_mul_f32_e32 v3, v7, v47
	v_mul_f32_e32 v4, v9, v45
	v_fmac_f32_e32 v3, v6, v43
	v_fmac_f32_e32 v4, v8, v41
	v_add_f32_e32 v3, v3, v4
	v_add_f32_e32 v2, v2, v3
	s_waitcnt lgkmcnt(1)
	v_mul_f32_e32 v3, v53, v42
	v_mul_f32_e32 v4, v55, v40
	v_fmac_f32_e32 v3, v52, v39
	v_fmac_f32_e32 v4, v54, v37
	v_add_f32_e32 v3, v3, v4
	v_add_f32_e32 v2, v2, v3
	s_waitcnt lgkmcnt(0)
	v_mul_f32_e32 v3, v57, v38
	v_mul_f32_e32 v4, v59, v36
	v_fmac_f32_e32 v3, v56, v33
	v_fmac_f32_e32 v4, v58, v35
	v_add_f32_e32 v3, v3, v4
	v_add_f32_e32 v51, v2, v3
	ds_read_b128 v[52:55], v34 offset:8192
	ds_read_b128 v[56:59], v34 offset:8208
	ds_read_b128 v[6:9], v34 offset:10240
	ds_read_b128 v[2:5], v34 offset:10256
	s_waitcnt lgkmcnt(3)
	v_mul_f32_e32 v53, v53, v49
	v_fmac_f32_e32 v53, v52, v46
	v_mul_f32_e32 v52, v55, v48
	v_fmac_f32_e32 v52, v54, v44
	v_add_f32_e32 v52, v53, v52
	s_waitcnt lgkmcnt(2)
	v_mul_f32_e32 v53, v57, v47
	v_mul_f32_e32 v54, v59, v45
	s_waitcnt lgkmcnt(1)
	v_mul_f32_e32 v7, v7, v42
	v_fmac_f32_e32 v53, v56, v43
	v_fmac_f32_e32 v54, v58, v41
	v_fmac_f32_e32 v7, v6, v39
	v_mul_f32_e32 v6, v9, v40
	s_waitcnt lgkmcnt(0)
	v_mul_f32_e32 v3, v3, v38
	v_add_f32_e32 v53, v53, v54
	v_fmac_f32_e32 v6, v8, v37
	v_fmac_f32_e32 v3, v2, v33
	v_mul_f32_e32 v2, v5, v36
	v_add_f32_e32 v52, v52, v53
	v_add_f32_e32 v6, v7, v6
	v_fmac_f32_e32 v2, v4, v35
	v_add_f32_e32 v6, v52, v6
	v_add_f32_e32 v2, v3, v2
	v_add_f32_e32 v60, v6, v2
	ds_read_b128 v[2:5], v34 offset:12288
	ds_read_b128 v[6:9], v34 offset:12304
	ds_read_b128 v[52:55], v34 offset:14336
	ds_read_b128 v[56:59], v34 offset:14352
	s_waitcnt lgkmcnt(3)
	v_mul_f32_e32 v3, v3, v49
	v_fmac_f32_e32 v3, v2, v46
	v_mul_f32_e32 v2, v5, v48
	v_fmac_f32_e32 v2, v4, v44
	v_add_f32_e32 v2, v3, v2
	s_waitcnt lgkmcnt(2)
	v_mul_f32_e32 v3, v7, v47
	v_mul_f32_e32 v4, v9, v45
	v_fmac_f32_e32 v3, v6, v43
	v_fmac_f32_e32 v4, v8, v41
	v_add_f32_e32 v3, v3, v4
	v_add_f32_e32 v2, v2, v3
	s_waitcnt lgkmcnt(1)
	v_mul_f32_e32 v3, v53, v42
	v_mul_f32_e32 v4, v55, v40
	v_fmac_f32_e32 v3, v52, v39
	v_fmac_f32_e32 v4, v54, v37
	v_add_f32_e32 v3, v3, v4
	v_add_f32_e32 v2, v2, v3
	s_waitcnt lgkmcnt(0)
	v_mul_f32_e32 v3, v57, v38
	v_mul_f32_e32 v4, v59, v36
	v_fmac_f32_e32 v3, v56, v33
	v_fmac_f32_e32 v4, v58, v35
	v_add_f32_e32 v3, v3, v4
	v_add_f32_e32 v61, v2, v3
	ds_read_b128 v[2:5], v34 offset:16384
	ds_read_b128 v[6:9], v34 offset:16400
	ds_read_b128 v[52:55], v34 offset:18432
	ds_read_b128 v[56:59], v34 offset:18448
	s_waitcnt lgkmcnt(3)
	v_mul_f32_e32 v3, v3, v49
	v_fmac_f32_e32 v3, v2, v46
	v_mul_f32_e32 v2, v5, v48
	v_fmac_f32_e32 v2, v4, v44
	v_add_f32_e32 v2, v3, v2
	s_waitcnt lgkmcnt(2)
	v_mul_f32_e32 v3, v7, v47
	v_mul_f32_e32 v4, v9, v45
	v_fmac_f32_e32 v3, v6, v43
	v_fmac_f32_e32 v4, v8, v41
	v_add_f32_e32 v3, v3, v4
	v_add_f32_e32 v2, v2, v3
	s_waitcnt lgkmcnt(1)
	v_mul_f32_e32 v3, v53, v42
	v_mul_f32_e32 v4, v55, v40
	v_fmac_f32_e32 v3, v52, v39
	v_fmac_f32_e32 v4, v54, v37
	v_add_f32_e32 v3, v3, v4
	v_add_f32_e32 v2, v2, v3
	s_waitcnt lgkmcnt(0)
	v_mul_f32_e32 v3, v57, v38
	v_mul_f32_e32 v4, v59, v36
	v_fmac_f32_e32 v3, v56, v33
	v_fmac_f32_e32 v4, v58, v35
	v_add_f32_e32 v3, v3, v4
	v_add_f32_e32 v62, v2, v3
	ds_read_b128 v[2:5], v34 offset:20480
	ds_read_b128 v[6:9], v34 offset:20496
	ds_read_b128 v[52:55], v34 offset:22528
	ds_read_b128 v[56:59], v34 offset:22544
	s_waitcnt lgkmcnt(3)
	v_mul_f32_e32 v3, v3, v49
	v_fmac_f32_e32 v3, v2, v46
	v_mul_f32_e32 v2, v5, v48
	v_fmac_f32_e32 v2, v4, v44
	v_add_f32_e32 v2, v3, v2
	s_waitcnt lgkmcnt(2)
	v_mul_f32_e32 v3, v7, v47
	v_mul_f32_e32 v4, v9, v45
	v_fmac_f32_e32 v3, v6, v43
	v_fmac_f32_e32 v4, v8, v41
	v_add_f32_e32 v3, v3, v4
	v_add_f32_e32 v2, v2, v3
	s_waitcnt lgkmcnt(1)
; #define LAS __attribute__((address_space(3)))
; __device__ __forceinline__ float log_sigmoid_f(float x) { return fminf(x, 0.f) - log1pf(__expf(-fabsf(x))); }
; __device__ __forceinline__ void f_phase(int l, LAS unsigned char* lds, int vcu, int G, int tid, int wave, int lane) {
;     ...
;             for (int hh = 0; hh < 8; ++hh) { const LAS f32x4* w = (const LAS f32x4*)(wfs + hh * 1024 + 8 * lane);
;                 const f32x4 w0 = w[0], w1 = w[1], w2 = w[128], w3 = w[129];
;                 float p = ((h0.x * w0.x + h0.y * w0.y) + (h0.z * w0.z + h0.w * w0.w)) + ((h1.x * w1.x + h1.y * w1.y) + (h1.z * w1.z + h1.w * w1.w))
;                         + ((h2.x * w2.x + h2.y * w2.y) + (h2.z * w2.z + h2.w * w2.w)) + ((h3.x * w3.x + h3.y * w3.y) + (h3.z * w3.z + h3.w * w3.w));
;                 p8[hh] = p; }
;             { const bool b32 = (lane & 32) != 0, b16 = (lane & 16) != 0, b8 = (lane & 8) != 0; float q4[4], q2[2], q1;
; #pragma unroll
;               for (int k = 0; k < 4; ++k) { const float mine = b32 ? p8[4 + k] : p8[k], send = b32 ? p8[k] : p8[4 + k]; q4[k] = mine + __shfl_xor(send, 32); }
; #pragma unroll
;               for (int k = 0; k < 2; ++k) { const float mine = b16 ? q4[2 + k] : q4[k], send = b16 ? q4[k] : q4[2 + k]; q2[k] = mine + __shfl_xor(send, 16); }
;               { const float mine = b8 ? q2[1] : q2[0], send = b8 ? q2[0] : q2[1]; q1 = mine + __shfl_xor(send, 8); }
;               q1 += __shfl_xor(q1, 4); q1 += __shfl_xor(q1, 2); q1 += __shfl_xor(q1, 1);
;               if ((lane & 7) == 0) lfs[rl * 8 + (lane >> 3)] = log_sigmoid_f(q1 + fb[lane >> 3]); } }
	v_mul_f32_e32 v3, v53, v42
	v_mul_f32_e32 v4, v55, v40
	v_fmac_f32_e32 v3, v52, v39
	v_fmac_f32_e32 v4, v54, v37
	v_add_f32_e32 v3, v3, v4
	v_add_f32_e32 v2, v2, v3
	s_waitcnt lgkmcnt(0)
	v_mul_f32_e32 v3, v57, v38
	v_mul_f32_e32 v4, v59, v36
	v_fmac_f32_e32 v3, v56, v33
	v_fmac_f32_e32 v4, v58, v35
	v_add_f32_e32 v3, v3, v4
	v_add_f32_e32 v63, v2, v3
	ds_read_b128 v[2:5], v34 offset:24576
	ds_read_b128 v[6:9], v34 offset:24592
	ds_read_b128 v[52:55], v34 offset:26624
	ds_read_b128 v[56:59], v34 offset:26640
	s_waitcnt lgkmcnt(3)
	v_mul_f32_e32 v3, v3, v49
	v_fmac_f32_e32 v3, v2, v46
	v_mul_f32_e32 v2, v5, v48
	v_fmac_f32_e32 v2, v4, v44
	v_add_f32_e32 v2, v3, v2
	s_waitcnt lgkmcnt(2)
	v_mul_f32_e32 v3, v7, v47
	v_mul_f32_e32 v4, v9, v45
	v_fmac_f32_e32 v3, v6, v43
	v_fmac_f32_e32 v4, v8, v41
	v_add_f32_e32 v3, v3, v4
	v_add_f32_e32 v2, v2, v3
	s_waitcnt lgkmcnt(1)
	v_mul_f32_e32 v3, v53, v42
	v_mul_f32_e32 v4, v55, v40
	v_fmac_f32_e32 v3, v52, v39
	v_fmac_f32_e32 v4, v54, v37
	v_add_f32_e32 v3, v3, v4
	v_add_f32_e32 v2, v2, v3
	s_waitcnt lgkmcnt(0)
	v_mul_f32_e32 v3, v57, v38
	v_mul_f32_e32 v4, v59, v36
	v_fmac_f32_e32 v3, v56, v33
	v_fmac_f32_e32 v4, v58, v35
	v_add_f32_e32 v3, v3, v4
	v_add_f32_e32 v64, v2, v3
	ds_read_b128 v[2:5], v34 offset:28672
	ds_read_b128 v[6:9], v34 offset:28688
	ds_read_b128 v[52:55], v34 offset:30720
	ds_read_b128 v[56:59], v34 offset:30736
	s_waitcnt lgkmcnt(3)
	v_mul_f32_e32 v3, v3, v49
	v_fmac_f32_e32 v3, v2, v46
	v_mul_f32_e32 v2, v5, v48
	v_fmac_f32_e32 v2, v4, v44
	v_add_f32_e32 v2, v3, v2
	s_waitcnt lgkmcnt(2)
	v_mul_f32_e32 v3, v7, v47
	v_mul_f32_e32 v4, v9, v45
	v_fmac_f32_e32 v3, v6, v43
	v_fmac_f32_e32 v4, v8, v41
	v_add_f32_e32 v3, v3, v4
	v_add_f32_e32 v2, v2, v3
	s_waitcnt lgkmcnt(1)
	v_mul_f32_e32 v3, v53, v42
	v_mul_f32_e32 v4, v55, v40
	v_fmac_f32_e32 v3, v52, v39
	v_fmac_f32_e32 v4, v54, v37
	v_add_f32_e32 v3, v3, v4
	v_add_f32_e32 v2, v2, v3
	s_waitcnt lgkmcnt(0)
	v_mul_f32_e32 v3, v57, v38
	v_mul_f32_e32 v4, v59, v36
	v_fmac_f32_e32 v3, v56, v33
	v_fmac_f32_e32 v4, v58, v35
	v_add_f32_e32 v3, v3, v4
	v_cndmask_b32_e32 v4, v50, v62, vcc
	ds_bpermute_b32 v4, v20, v4
	v_cndmask_b32_e32 v5, v51, v63, vcc
	ds_bpermute_b32 v5, v20, v5
	v_cndmask_b32_e32 v6, v60, v64, vcc
	ds_bpermute_b32 v6, v20, v6
	v_add_f32_e32 v2, v2, v3
	v_cndmask_b32_e32 v3, v62, v50, vcc
	s_waitcnt lgkmcnt(2)
	v_add_f32_e32 v3, v3, v4
	v_cndmask_b32_e32 v4, v63, v51, vcc
	s_waitcnt lgkmcnt(1)
	v_add_f32_e32 v4, v4, v5
	v_cndmask_b32_e32 v5, v64, v60, vcc
	s_waitcnt lgkmcnt(0)
	v_add_f32_e32 v5, v5, v6
	v_cndmask_b32_e32 v6, v2, v61, vcc
	v_cndmask_b32_e32 v2, v61, v2, vcc
	ds_bpermute_b32 v2, v20, v2
	v_add_u32_e32 v33, s25, v0
	s_waitcnt lgkmcnt(0)
	v_add_f32_e32 v2, v6, v2
	v_cndmask_b32_e64 v6, v5, v3, s[4:5]
	v_cndmask_b32_e64 v3, v3, v5, s[4:5]
	v_cndmask_b32_e64 v5, v2, v4, s[4:5]
	v_cndmask_b32_e64 v2, v4, v2, s[4:5]
	ds_bpermute_b32 v3, v21, v3
	ds_bpermute_b32 v2, v21, v2
	s_waitcnt lgkmcnt(1)
	v_add_f32_e32 v3, v6, v3
	s_waitcnt lgkmcnt(0)
	v_add_f32_e32 v2, v5, v2
	v_cndmask_b32_e64 v4, v2, v3, s[6:7]
	v_cndmask_b32_e64 v2, v3, v2, s[6:7]
	ds_bpermute_b32 v2, v22, v2
	s_waitcnt lgkmcnt(0)
	v_add_f32_e32 v2, v4, v2
	ds_bpermute_b32 v3, v23, v2
	s_waitcnt lgkmcnt(0)
	v_add_f32_e32 v2, v2, v3
	ds_bpermute_b32 v3, v24, v2
	s_waitcnt lgkmcnt(0)
	v_add_f32_e32 v2, v2, v3
	ds_bpermute_b32 v3, v25, v2
	s_and_saveexec_b64 s[28:29], s[8:9]
	s_cbranch_execz .LBB0_494
	s_waitcnt lgkmcnt(0)
	v_add_f32_e32 v2, v2, v3
	v_mov_b32_e32 v3, v100
	s_mov_b32 s0, 0xbfb8aa3b
	s_waitcnt vmcnt(0)
	v_add_f32_e32 v3, v2, v3
	v_min_f32_e32 v2, 0, v3
	v_mul_f32_e64 v3, |v3|, s0
	v_exp_f32_e32 v3, v3
	s_nop 0
	v_add_f32_e32 v6, 1.0, v3
	v_add_f32_e32 v4, -1.0, v6
	v_sub_f32_e32 v5, v4, v6
	v_add_f32_e32 v5, 1.0, v5
	v_sub_f32_e32 v4, v3, v4
	v_add_f32_e32 v7, v4, v5
	v_frexp_mant_f32_e32 v4, v6
	v_cmp_gt_f32_e64 s[22:23], s76, v4
	v_cvt_f64_f32_e32 v[4:5], v6
	v_frexp_exp_i32_f64_e32 v4, v[4:5]
	v_subbrev_co_u32_e64 v35, s[22:23], 0, v4, s[22:23]
	v_sub_u32_e32 v4, 0, v35
	v_ldexp_f32 v5, v6, v4
	v_add_f32_e32 v6, -1.0, v5
	v_add_f32_e32 v8, 1.0, v5
	v_ldexp_f32 v4, v7, v4
	v_add_f32_e32 v7, 1.0, v6
	v_add_f32_e32 v9, -1.0, v8
	v_sub_f32_e32 v7, v5, v7
	v_sub_f32_e32 v5, v5, v9
	v_add_f32_e32 v7, v4, v7
	v_add_f32_e32 v4, v4, v5
	v_add_f32_e32 v38, v8, v4
	v_rcp_f32_e32 v40, v38
	v_sub_f32_e32 v5, v38, v8
	v_sub_f32_e32 v39, v4, v5
	v_add_f32_e32 v5, v6, v7
	v_mul_f32_e32 v42, v5, v40
	v_sub_f32_e32 v4, v5, v6
	v_mul_f32_e32 v6, v38, v42
	v_fma_f32 v8, v42, v38, -v6
	v_fmac_f32_e32 v8, v42, v39
	v_sub_f32_e32 v41, v7, v4
	v_add_f32_e32 v4, v6, v8
	v_sub_f32_e32 v7, v5, v4
	v_pk_add_f32 v[36:37], v[4:5], v[6:7] neg_lo:[0,1] neg_hi:[0,1]
	v_mov_b32_e32 v9, v4
	v_pk_add_f32 v[4:5], v[36:37], v[8:9] neg_lo:[0,1] neg_hi:[0,1]
	v_cmp_neq_f32_e64 s[22:23], s82, v3
	v_add_f32_e32 v5, v41, v5
	v_add_f32_e32 v4, v4, v5
	v_add_f32_e32 v5, v7, v4
	v_mul_f32_e32 v41, v40, v5
	v_mul_f32_e32 v6, v38, v41
	v_fma_f32 v8, v41, v38, -v6
	v_fmac_f32_e32 v8, v41, v39
	v_sub_f32_e32 v7, v7, v5
	v_add_f32_e32 v38, v4, v7
	v_add_f32_e32 v4, v6, v8
	v_sub_f32_e32 v7, v5, v4
	v_pk_add_f32 v[36:37], v[4:5], v[6:7] neg_lo:[0,1] neg_hi:[0,1]
	v_mov_b32_e32 v9, v4
	v_pk_add_f32 v[4:5], v[36:37], v[8:9] neg_lo:[0,1] neg_hi:[0,1]
	s_nop 0
	v_add_f32_e32 v5, v38, v5
	v_add_f32_e32 v4, v4, v5
	v_add_f32_e32 v5, v42, v41
	v_add_f32_e32 v4, v7, v4
	v_sub_f32_e32 v6, v5, v42
	v_mul_f32_e32 v4, v40, v4
	v_sub_f32_e32 v6, v41, v6
	v_add_f32_e32 v6, v6, v4
	v_add_f32_e32 v8, v5, v6
	v_mul_f32_e32 v9, v8, v8
	v_fmamk_f32 v4, v9, 0x3e9b6dac, v233
	v_fmaak_f32 v217, v9, v4, 0x3f2aaada
; #define LAS __attribute__((address_space(3)))
; __device__ __forceinline__ void f_phase(int l, LAS unsigned char* lds, int vcu, int G, int tid, int wave, int lane) {
;     ...
;         for (int i = 0; i < 8; ++i) { const int rl = wave * 8 + i, row = blk * 64 + rl;
;             const v4u* xr = (const v4u*)(XN + (size_t)row * 1024) + lane;
;             const v4u a = xr[0], c = xr[64];
;             const f32x4 h0 = {__uint_as_float(a.x << 16), __uint_as_float(a.x & 0xffff0000u), __uint_as_float(a.y << 16), __uint_as_float(a.y & 0xffff0000u)};
;             const f32x4 h1 = {__uint_as_float(a.z << 16), __uint_as_float(a.z & 0xffff0000u), __uint_as_float(a.w << 16), __uint_as_float(a.w & 0xffff0000u)};
;             const f32x4 h2 = {__uint_as_float(c.x << 16), __uint_as_float(c.x & 0xffff0000u), __uint_as_float(c.y << 16), __uint_as_float(c.y & 0xffff0000u)};
;             const f32x4 h3 = {__uint_as_float(c.z << 16), __uint_as_float(c.z & 0xffff0000u), __uint_as_float(c.w << 16), __uint_as_float(c.w & 0xffff0000u)};
;             float p8[8];
; #pragma unroll
;             for (int hh = 0; hh < 8; ++hh) { const LAS f32x4* w = (const LAS f32x4*)(wfs + hh * 1024 + 8 * lane);
;                 const f32x4 w0 = w[0], w1 = w[1], w2 = w[128], w3 = w[129];
;                 float p = ((h0.x * w0.x + h0.y * w0.y) + (h0.z * w0.z + h0.w * w0.w)) + ((h1.x * w1.x + h1.y * w1.y) + (h1.z * w1.z + h1.w * w1.w))
;                         + ((h2.x * w2.x + h2.y * w2.y) + (h2.z * w2.z + h2.w * w2.w)) + ((h3.x * w3.x + h3.y * w3.y) + (h3.z * w3.z + h3.w * w3.w));
;                 p8[hh] = p; }
;             { const bool b32 = (lane & 32) != 0, b16 = (lane & 16) != 0, b8 = (lane & 8) != 0; float q4[4], q2[2], q1;
; #pragma unroll
;               for (int k = 0; k < 4; ++k) { const float mine = b32 ? p8[4 + k] : p8[k], send = b32 ? p8[k] : p8[4 + k]; q4[k] = mine + __shfl_xor(send, 32); }
; #pragma unroll
;               for (int k = 0; k < 2; ++k) { const float mine = b16 ? q4[2 + k] : q4[k], send = b16 ? q4[k] : q4[2 + k]; q2[k] = mine + __shfl_xor(send, 16); }
;               { const float mine = b8 ? q2[1] : q2[0], send = b8 ? q2[0] : q2[1]; q1 = mine + __shfl_xor(send, 8); }
;               q1 += __shfl_xor(q1, 4); q1 += __shfl_xor(q1, 2); q1 += __shfl_xor(q1, 1);
;               if ((lane & 7) == 0) lfs[rl * 8 + (lane >> 3)] = log_sigmoid_f(q1 + fb[lane >> 3]); } }
	v_cvt_f32_i32_e32 v4, v35
	v_sub_f32_e32 v5, v8, v5
	v_sub_f32_e32 v5, v6, v5
	v_ldexp_f32 v35, v5, 1
	v_mul_f32_e32 v5, v8, v9
	v_ldexp_f32 v7, v8, 1
	v_pk_mul_f32 v[8:9], v[4:5], v[216:217]
	s_nop 0
	v_fma_f32 v6, v4, s81, -v8
	v_fmac_f32_e32 v6, 0xb102e308, v4
	v_pk_add_f32 v[4:5], v[8:9], v[6:7]
	v_mov_b32_e32 v36, v8
	v_sub_f32_e32 v7, v5, v7
	v_sub_f32_e32 v7, v9, v7
	v_add_f32_e32 v37, v35, v7
	v_pk_add_f32 v[8:9], v[4:5], v[8:9] neg_lo:[0,1] neg_hi:[0,1]
	v_pk_add_f32 v[38:39], v[4:5], v[36:37]
	v_mov_b32_e32 v7, v4
	v_mov_b32_e32 v9, v39
	v_pk_add_f32 v[40:41], v[6:7], v[8:9] neg_lo:[0,1] neg_hi:[0,1]
	v_pk_add_f32 v[6:7], v[6:7], v[8:9]
	v_mov_b32_e32 v36, v37
	v_pk_add_f32 v[8:9], v[6:7], v[4:5] op_sel:[1,0] op_sel_hi:[0,1] neg_lo:[0,1] neg_hi:[0,1]
	v_pk_add_f32 v[42:43], v[38:39], v[8:9] op_sel_hi:[1,0] neg_lo:[0,1] neg_hi:[0,1]
	v_mov_b32_e32 v38, v39
	v_mov_b32_e32 v39, v7
	v_pk_mov_b32 v[8:9], v[4:5], v[8:9] op_sel:[1,0]
	v_mov_b32_e32 v37, v4
	v_pk_add_f32 v[8:9], v[38:39], v[8:9] neg_lo:[0,1] neg_hi:[0,1]
	v_mov_b32_e32 v42, v40
	v_pk_add_f32 v[4:5], v[36:37], v[8:9] neg_lo:[0,1] neg_hi:[0,1]
	v_mov_b32_e32 v41, v7
	v_pk_add_f32 v[8:9], v[42:43], v[4:5]
	s_nop 0
	v_pk_add_f32 v[36:37], v[8:9], v[8:9] op_sel:[0,1] op_sel_hi:[1,0]
	s_nop 0
	v_pk_add_f32 v[6:7], v[6:7], v[36:37] op_sel:[1,0] op_sel_hi:[0,1]
	v_mov_b32_e32 v9, v6
	v_pk_add_f32 v[38:39], v[8:9], v[40:41] neg_lo:[0,1] neg_hi:[0,1]
	v_mov_b32_e32 v5, v36
	v_sub_f32_e32 v7, v8, v38
	v_pk_add_f32 v[4:5], v[4:5], v[38:39] neg_lo:[0,1] neg_hi:[0,1]
	v_sub_f32_e32 v7, v40, v7
	v_add_f32_e32 v4, v4, v7
	v_add_f32_e32 v4, v4, v5
	v_add_f32_e32 v4, v6, v4
	v_cndmask_b32_e64 v4, v239, v4, s[22:23]
	v_cmp_ngt_f32_e64 s[22:23], -1.0, v3
	s_nop 1
	v_cndmask_b32_e64 v4, v218, v4, s[22:23]
	v_cmp_neq_f32_e64 s[22:23], -1.0, v3
	s_nop 1
	v_cndmask_b32_e64 v4, v238, v4, s[22:23]
	v_cmp_lt_f32_e64 s[22:23], |v3|, s83
	s_nop 1
	v_cndmask_b32_e64 v3, v4, v3, s[22:23]
	v_sub_f32_e32 v2, v2, v3
	ds_write_b32 v33, v2
.LBB0_494:
	s_or_b64 exec, exec, s[28:29]
	s_ashr_i32 s27, s26, 31
	s_lshl_b64 s[0:1], s[26:27], 11
	v_lshl_add_u64 v[6:7], v[12:13], 0, s[0:1]
	s_waitcnt lgkmcnt(0)
	global_load_dwordx4 v[2:5], v[6:7], off
	s_nop 0
	global_load_dwordx4 v[6:9], v[6:7], off offset:1024
	s_waitcnt vmcnt(1)
	v_lshlrev_b32_e32 v47, 16, v2
	v_and_b32_e32 v50, 0xffff0000, v2
	v_lshlrev_b32_e32 v45, 16, v3
	v_and_b32_e32 v49, 0xffff0000, v3
	v_lshlrev_b32_e32 v44, 16, v4
	v_and_b32_e32 v48, 0xffff0000, v4
	v_lshlrev_b32_e32 v42, 16, v5
	v_and_b32_e32 v46, 0xffff0000, v5
	s_waitcnt vmcnt(0)
	v_lshlrev_b32_e32 v40, 16, v6
	v_and_b32_e32 v43, 0xffff0000, v6
	v_lshlrev_b32_e32 v38, 16, v7
	v_and_b32_e32 v41, 0xffff0000, v7
	v_lshlrev_b32_e32 v35, 16, v8
	v_and_b32_e32 v39, 0xffff0000, v8
	v_lshlrev_b32_e32 v36, 16, v9
	v_and_b32_e32 v37, 0xffff0000, v9
	ds_read_b128 v[2:5], v34
	ds_read_b128 v[6:9], v34 offset:16
	ds_read_b128 v[52:55], v34 offset:2048
	ds_read_b128 v[56:59], v34 offset:2064
	s_waitcnt lgkmcnt(3)
	v_mul_f32_e32 v3, v3, v50
	v_fmac_f32_e32 v3, v2, v47
	v_mul_f32_e32 v2, v5, v49
	v_fmac_f32_e32 v2, v4, v45
	v_add_f32_e32 v2, v3, v2
	s_waitcnt lgkmcnt(2)
	v_mul_f32_e32 v3, v7, v48
	v_mul_f32_e32 v4, v9, v46
	v_fmac_f32_e32 v3, v6, v44
	v_fmac_f32_e32 v4, v8, v42
	v_add_f32_e32 v3, v3, v4
	v_add_f32_e32 v2, v2, v3
	s_waitcnt lgkmcnt(1)
	v_mul_f32_e32 v3, v53, v43
	v_mul_f32_e32 v4, v55, v41
	v_fmac_f32_e32 v3, v52, v40
	v_fmac_f32_e32 v4, v54, v38
	v_add_f32_e32 v3, v3, v4
	v_add_f32_e32 v2, v2, v3
	s_waitcnt lgkmcnt(0)
	v_mul_f32_e32 v3, v57, v39
	v_mul_f32_e32 v4, v59, v37
	v_fmac_f32_e32 v3, v56, v35
	v_fmac_f32_e32 v4, v58, v36
	v_add_f32_e32 v3, v3, v4
	v_add_f32_e32 v51, v2, v3
	ds_read_b128 v[2:5], v34 offset:4096
	ds_read_b128 v[6:9], v34 offset:4112
	ds_read_b128 v[52:55], v34 offset:6144
	ds_read_b128 v[56:59], v34 offset:6160
	s_waitcnt lgkmcnt(3)
	v_mul_f32_e32 v3, v3, v50
	v_fmac_f32_e32 v3, v2, v47
	v_mul_f32_e32 v2, v5, v49
	v_fmac_f32_e32 v2, v4, v45
	v_add_f32_e32 v2, v3, v2
	s_waitcnt lgkmcnt(2)
	v_mul_f32_e32 v3, v7, v48
	v_mul_f32_e32 v4, v9, v46
	v_fmac_f32_e32 v3, v6, v44
	v_fmac_f32_e32 v4, v8, v42
	v_add_f32_e32 v3, v3, v4
	v_add_f32_e32 v2, v2, v3
	s_waitcnt lgkmcnt(1)
	v_mul_f32_e32 v3, v53, v43
	v_mul_f32_e32 v4, v55, v41
	v_fmac_f32_e32 v3, v52, v40
	v_fmac_f32_e32 v4, v54, v38
	v_add_f32_e32 v3, v3, v4
	v_add_f32_e32 v2, v2, v3
	s_waitcnt lgkmcnt(0)
	v_mul_f32_e32 v3, v57, v39
	v_mul_f32_e32 v4, v59, v37
	v_fmac_f32_e32 v3, v56, v35
	v_fmac_f32_e32 v4, v58, v36
	v_add_f32_e32 v3, v3, v4
	v_add_f32_e32 v52, v2, v3
	ds_read_b128 v[54:57], v34 offset:8192
	ds_read_b128 v[58:61], v34 offset:8208
	ds_read_b128 v[6:9], v34 offset:10240
	ds_read_b128 v[2:5], v34 offset:10256
	s_waitcnt lgkmcnt(3)
	v_mul_f32_e32 v53, v55, v50
	v_fmac_f32_e32 v53, v54, v47
	v_mul_f32_e32 v54, v57, v49
	v_fmac_f32_e32 v54, v56, v45
	v_add_f32_e32 v53, v53, v54
	s_waitcnt lgkmcnt(2)
	v_mul_f32_e32 v54, v59, v48
	v_mul_f32_e32 v55, v61, v46
	s_waitcnt lgkmcnt(1)
	v_mul_f32_e32 v7, v7, v43
	v_fmac_f32_e32 v54, v58, v44
	v_fmac_f32_e32 v55, v60, v42
	v_fmac_f32_e32 v7, v6, v40
	v_mul_f32_e32 v6, v9, v41
	s_waitcnt lgkmcnt(0)
	v_mul_f32_e32 v3, v3, v39
	v_add_f32_e32 v54, v54, v55
	v_fmac_f32_e32 v6, v8, v38
	v_fmac_f32_e32 v3, v2, v35
	v_mul_f32_e32 v2, v5, v37
	v_add_f32_e32 v53, v53, v54
	v_add_f32_e32 v6, v7, v6
	v_fmac_f32_e32 v2, v4, v36
	v_add_f32_e32 v6, v53, v6
	v_add_f32_e32 v2, v3, v2
	v_add_f32_e32 v53, v6, v2
	ds_read_b128 v[2:5], v34 offset:12288
	ds_read_b128 v[6:9], v34 offset:12304
	ds_read_b128 v[54:57], v34 offset:14336
	ds_read_b128 v[58:61], v34 offset:14352
	s_waitcnt lgkmcnt(3)
; #define LAS __attribute__((address_space(3)))
; __device__ __forceinline__ void f_phase(int l, LAS unsigned char* lds, int vcu, int G, int tid, int wave, int lane) {
;     ...
;             for (int hh = 0; hh < 8; ++hh) { const LAS f32x4* w = (const LAS f32x4*)(wfs + hh * 1024 + 8 * lane);
;                 const f32x4 w0 = w[0], w1 = w[1], w2 = w[128], w3 = w[129];
;                 float p = ((h0.x * w0.x + h0.y * w0.y) + (h0.z * w0.z + h0.w * w0.w)) + ((h1.x * w1.x + h1.y * w1.y) + (h1.z * w1.z + h1.w * w1.w))
;                         + ((h2.x * w2.x + h2.y * w2.y) + (h2.z * w2.z + h2.w * w2.w)) + ((h3.x * w3.x + h3.y * w3.y) + (h3.z * w3.z + h3.w * w3.w));
;                 p8[hh] = p; }
;             { const bool b32 = (lane & 32) != 0, b16 = (lane & 16) != 0, b8 = (lane & 8) != 0; float q4[4], q2[2], q1;
; #pragma unroll
;               for (int k = 0; k < 4; ++k) { const float mine = b32 ? p8[4 + k] : p8[k], send = b32 ? p8[k] : p8[4 + k]; q4[k] = mine + __shfl_xor(send, 32); }
; #pragma unroll
;               for (int k = 0; k < 2; ++k) { const float mine = b16 ? q4[2 + k] : q4[k], send = b16 ? q4[k] : q4[2 + k]; q2[k] = mine + __shfl_xor(send, 16); }
;               { const float mine = b8 ? q2[1] : q2[0], send = b8 ? q2[0] : q2[1]; q1 = mine + __shfl_xor(send, 8); }
;               q1 += __shfl_xor(q1, 4); q1 += __shfl_xor(q1, 2); q1 += __shfl_xor(q1, 1);
	v_mul_f32_e32 v3, v3, v50
	v_fmac_f32_e32 v3, v2, v47
	v_mul_f32_e32 v2, v5, v49
	v_fmac_f32_e32 v2, v4, v45
	v_add_f32_e32 v2, v3, v2
	s_waitcnt lgkmcnt(2)
	v_mul_f32_e32 v3, v7, v48
	v_mul_f32_e32 v4, v9, v46
	v_fmac_f32_e32 v3, v6, v44
	v_fmac_f32_e32 v4, v8, v42
	v_add_f32_e32 v3, v3, v4
	v_add_f32_e32 v2, v2, v3
	s_waitcnt lgkmcnt(1)
	v_mul_f32_e32 v3, v55, v43
	v_mul_f32_e32 v4, v57, v41
	v_fmac_f32_e32 v3, v54, v40
	v_fmac_f32_e32 v4, v56, v38
	v_add_f32_e32 v3, v3, v4
	v_add_f32_e32 v2, v2, v3
	s_waitcnt lgkmcnt(0)
	v_mul_f32_e32 v3, v59, v39
	v_mul_f32_e32 v4, v61, v37
	v_fmac_f32_e32 v3, v58, v35
	v_fmac_f32_e32 v4, v60, v36
	v_add_f32_e32 v3, v3, v4
	v_add_f32_e32 v62, v2, v3
	ds_read_b128 v[2:5], v34 offset:16384
	ds_read_b128 v[6:9], v34 offset:16400
	ds_read_b128 v[54:57], v34 offset:18432
	ds_read_b128 v[58:61], v34 offset:18448
	s_waitcnt lgkmcnt(3)
	v_mul_f32_e32 v3, v3, v50
	v_fmac_f32_e32 v3, v2, v47
	v_mul_f32_e32 v2, v5, v49
	v_fmac_f32_e32 v2, v4, v45
	v_add_f32_e32 v2, v3, v2
	s_waitcnt lgkmcnt(2)
	v_mul_f32_e32 v3, v7, v48
	v_mul_f32_e32 v4, v9, v46
	v_fmac_f32_e32 v3, v6, v44
	v_fmac_f32_e32 v4, v8, v42
	v_add_f32_e32 v3, v3, v4
	v_add_f32_e32 v2, v2, v3
	s_waitcnt lgkmcnt(1)
	v_mul_f32_e32 v3, v55, v43
	v_mul_f32_e32 v4, v57, v41
	v_fmac_f32_e32 v3, v54, v40
	v_fmac_f32_e32 v4, v56, v38
	v_add_f32_e32 v3, v3, v4
	v_add_f32_e32 v2, v2, v3
	s_waitcnt lgkmcnt(0)
	v_mul_f32_e32 v3, v59, v39
	v_mul_f32_e32 v4, v61, v37
	v_fmac_f32_e32 v3, v58, v35
	v_fmac_f32_e32 v4, v60, v36
	v_add_f32_e32 v3, v3, v4
	v_add_f32_e32 v63, v2, v3
	ds_read_b128 v[2:5], v34 offset:20480
	ds_read_b128 v[6:9], v34 offset:20496
	ds_read_b128 v[54:57], v34 offset:22528
	ds_read_b128 v[58:61], v34 offset:22544
	s_waitcnt lgkmcnt(3)
	v_mul_f32_e32 v3, v3, v50
	v_fmac_f32_e32 v3, v2, v47
	v_mul_f32_e32 v2, v5, v49
	v_fmac_f32_e32 v2, v4, v45
	v_add_f32_e32 v2, v3, v2
	s_waitcnt lgkmcnt(2)
	v_mul_f32_e32 v3, v7, v48
	v_mul_f32_e32 v4, v9, v46
	v_fmac_f32_e32 v3, v6, v44
	v_fmac_f32_e32 v4, v8, v42
	v_add_f32_e32 v3, v3, v4
	v_add_f32_e32 v2, v2, v3
	s_waitcnt lgkmcnt(1)
	v_mul_f32_e32 v3, v55, v43
	v_mul_f32_e32 v4, v57, v41
	v_fmac_f32_e32 v3, v54, v40
	v_fmac_f32_e32 v4, v56, v38
	v_add_f32_e32 v3, v3, v4
	v_add_f32_e32 v2, v2, v3
	s_waitcnt lgkmcnt(0)
	v_mul_f32_e32 v3, v59, v39
	v_mul_f32_e32 v4, v61, v37
	v_fmac_f32_e32 v3, v58, v35
	v_fmac_f32_e32 v4, v60, v36
	v_add_f32_e32 v3, v3, v4
	v_add_f32_e32 v64, v2, v3
	ds_read_b128 v[2:5], v34 offset:24576
	ds_read_b128 v[6:9], v34 offset:24592
	ds_read_b128 v[54:57], v34 offset:26624
	ds_read_b128 v[58:61], v34 offset:26640
	s_waitcnt lgkmcnt(3)
	v_mul_f32_e32 v3, v3, v50
	v_fmac_f32_e32 v3, v2, v47
	v_mul_f32_e32 v2, v5, v49
	v_fmac_f32_e32 v2, v4, v45
	v_add_f32_e32 v2, v3, v2
	s_waitcnt lgkmcnt(2)
	v_mul_f32_e32 v3, v7, v48
	v_mul_f32_e32 v4, v9, v46
	v_fmac_f32_e32 v3, v6, v44
	v_fmac_f32_e32 v4, v8, v42
	v_add_f32_e32 v3, v3, v4
	v_add_f32_e32 v2, v2, v3
	s_waitcnt lgkmcnt(1)
	v_mul_f32_e32 v3, v55, v43
	v_mul_f32_e32 v4, v57, v41
	v_fmac_f32_e32 v3, v54, v40
	v_fmac_f32_e32 v4, v56, v38
	v_add_f32_e32 v3, v3, v4
	v_add_f32_e32 v2, v2, v3
	s_waitcnt lgkmcnt(0)
	v_mul_f32_e32 v3, v59, v39
	v_mul_f32_e32 v4, v61, v37
	v_fmac_f32_e32 v3, v58, v35
	v_fmac_f32_e32 v4, v60, v36
	v_add_f32_e32 v3, v3, v4
	v_add_f32_e32 v65, v2, v3
	ds_read_b128 v[2:5], v34 offset:28672
	ds_read_b128 v[6:9], v34 offset:28688
	ds_read_b128 v[54:57], v34 offset:30720
	ds_read_b128 v[58:61], v34 offset:30736
	s_waitcnt lgkmcnt(3)
	v_mul_f32_e32 v3, v3, v50
	v_fmac_f32_e32 v3, v2, v47
	v_mul_f32_e32 v2, v5, v49
	v_fmac_f32_e32 v2, v4, v45
	v_add_f32_e32 v2, v3, v2
	s_waitcnt lgkmcnt(2)
	v_mul_f32_e32 v3, v7, v48
	v_mul_f32_e32 v4, v9, v46
	v_fmac_f32_e32 v3, v6, v44
	v_fmac_f32_e32 v4, v8, v42
	v_add_f32_e32 v3, v3, v4
	v_add_f32_e32 v2, v2, v3
	s_waitcnt lgkmcnt(1)
	v_mul_f32_e32 v3, v55, v43
	v_mul_f32_e32 v4, v57, v41
	v_fmac_f32_e32 v3, v54, v40
	v_fmac_f32_e32 v4, v56, v38
	v_add_f32_e32 v3, v3, v4
	v_add_f32_e32 v2, v2, v3
	s_waitcnt lgkmcnt(0)
	v_mul_f32_e32 v3, v59, v39
	v_mul_f32_e32 v4, v61, v37
	v_fmac_f32_e32 v3, v58, v35
	v_fmac_f32_e32 v4, v60, v36
	v_add_f32_e32 v3, v3, v4
	v_cndmask_b32_e32 v4, v51, v63, vcc
	ds_bpermute_b32 v4, v20, v4
	v_cndmask_b32_e32 v5, v52, v64, vcc
	ds_bpermute_b32 v5, v20, v5
	v_cndmask_b32_e32 v6, v53, v65, vcc
	ds_bpermute_b32 v6, v20, v6
	v_add_f32_e32 v2, v2, v3
	v_cndmask_b32_e32 v3, v63, v51, vcc
	s_waitcnt lgkmcnt(2)
	v_add_f32_e32 v3, v3, v4
	v_cndmask_b32_e32 v4, v64, v52, vcc
	s_waitcnt lgkmcnt(1)
	v_add_f32_e32 v4, v4, v5
	v_cndmask_b32_e32 v5, v65, v53, vcc
	s_waitcnt lgkmcnt(0)
	v_add_f32_e32 v5, v5, v6
	v_cndmask_b32_e32 v6, v2, v62, vcc
	v_cndmask_b32_e32 v2, v62, v2, vcc
	ds_bpermute_b32 v2, v20, v2
	s_waitcnt lgkmcnt(0)
	v_add_f32_e32 v2, v6, v2
	v_cndmask_b32_e64 v6, v5, v3, s[4:5]
	v_cndmask_b32_e64 v3, v3, v5, s[4:5]
	v_cndmask_b32_e64 v5, v2, v4, s[4:5]
	v_cndmask_b32_e64 v2, v4, v2, s[4:5]
	ds_bpermute_b32 v3, v21, v3
	ds_bpermute_b32 v2, v21, v2
	s_waitcnt lgkmcnt(1)
	v_add_f32_e32 v3, v6, v3
	s_waitcnt lgkmcnt(0)
	v_add_f32_e32 v2, v5, v2
	v_cndmask_b32_e64 v4, v2, v3, s[6:7]
	v_cndmask_b32_e64 v2, v3, v2, s[6:7]
	ds_bpermute_b32 v2, v22, v2
	s_waitcnt lgkmcnt(0)
	v_add_f32_e32 v2, v4, v2
	ds_bpermute_b32 v3, v23, v2
	s_waitcnt lgkmcnt(0)
	v_add_f32_e32 v2, v2, v3
	ds_bpermute_b32 v3, v24, v2
	s_waitcnt lgkmcnt(0)
	v_add_f32_e32 v2, v2, v3
	ds_bpermute_b32 v3, v25, v2
	s_and_saveexec_b64 s[28:29], s[8:9]
	s_cbranch_execz .LBB0_491
; __device__ __forceinline__ float log_sigmoid_f(float x) { return fminf(x, 0.f) - log1pf(__expf(-fabsf(x))); }
; __device__ __forceinline__ void f_phase(int l, LAS unsigned char* lds, int vcu, int G, int tid, int wave, int lane) {
;     ...
;               if ((lane & 7) == 0) lfs[rl * 8 + (lane >> 3)] = log_sigmoid_f(q1 + fb[lane >> 3]); } }
	s_waitcnt lgkmcnt(0)
	v_add_f32_e32 v2, v2, v3
	v_mov_b32_e32 v3, v100
	s_mov_b32 s0, 0xbfb8aa3b
	s_waitcnt vmcnt(0)
	v_add_f32_e32 v3, v2, v3
	v_min_f32_e32 v2, 0, v3
	v_mul_f32_e64 v3, |v3|, s0
	v_exp_f32_e32 v3, v3
	s_nop 0
	v_add_f32_e32 v6, 1.0, v3
	v_add_f32_e32 v4, -1.0, v6
	v_sub_f32_e32 v5, v4, v6
	v_add_f32_e32 v5, 1.0, v5
	v_sub_f32_e32 v4, v3, v4
	v_add_f32_e32 v7, v4, v5
	v_frexp_mant_f32_e32 v4, v6
	v_cmp_gt_f32_e64 s[22:23], s76, v4
	v_cvt_f64_f32_e32 v[4:5], v6
	v_frexp_exp_i32_f64_e32 v4, v[4:5]
	v_subbrev_co_u32_e64 v36, s[22:23], 0, v4, s[22:23]
	v_sub_u32_e32 v4, 0, v36
	v_ldexp_f32 v5, v6, v4
	v_add_f32_e32 v6, -1.0, v5
	v_add_f32_e32 v8, 1.0, v5
	v_ldexp_f32 v4, v7, v4
	v_add_f32_e32 v7, 1.0, v6
	v_add_f32_e32 v9, -1.0, v8
	v_sub_f32_e32 v7, v5, v7
	v_sub_f32_e32 v5, v5, v9
	v_add_f32_e32 v7, v4, v7
	v_add_f32_e32 v4, v4, v5
	v_add_f32_e32 v37, v8, v4
	v_rcp_f32_e32 v39, v37
	v_sub_f32_e32 v5, v37, v8
	v_sub_f32_e32 v38, v4, v5
	v_add_f32_e32 v5, v6, v7
	v_mul_f32_e32 v41, v5, v39
	v_sub_f32_e32 v4, v5, v6
	v_mul_f32_e32 v6, v37, v41
	v_fma_f32 v8, v41, v37, -v6
	v_fmac_f32_e32 v8, v41, v38
	v_sub_f32_e32 v40, v7, v4
	v_add_f32_e32 v4, v6, v8
	v_sub_f32_e32 v7, v5, v4
	v_pk_add_f32 v[34:35], v[4:5], v[6:7] neg_lo:[0,1] neg_hi:[0,1]
	v_mov_b32_e32 v9, v4
	v_pk_add_f32 v[4:5], v[34:35], v[8:9] neg_lo:[0,1] neg_hi:[0,1]
	v_cmp_neq_f32_e64 s[22:23], s82, v3
	v_add_f32_e32 v5, v40, v5
	v_add_f32_e32 v4, v4, v5
	v_add_f32_e32 v5, v7, v4
	v_mul_f32_e32 v40, v39, v5
	v_mul_f32_e32 v6, v37, v40
	v_fma_f32 v8, v40, v37, -v6
	v_fmac_f32_e32 v8, v40, v38
	v_sub_f32_e32 v7, v7, v5
	v_add_f32_e32 v37, v4, v7
	v_add_f32_e32 v4, v6, v8
	v_sub_f32_e32 v7, v5, v4
	v_pk_add_f32 v[34:35], v[4:5], v[6:7] neg_lo:[0,1] neg_hi:[0,1]
	v_mov_b32_e32 v9, v4
	v_pk_add_f32 v[4:5], v[34:35], v[8:9] neg_lo:[0,1] neg_hi:[0,1]
	s_nop 0
	v_add_f32_e32 v5, v37, v5
	v_add_f32_e32 v4, v4, v5
	v_add_f32_e32 v5, v41, v40
	v_add_f32_e32 v4, v7, v4
	v_sub_f32_e32 v6, v5, v41
	v_mul_f32_e32 v4, v39, v4
	v_sub_f32_e32 v6, v40, v6
	v_add_f32_e32 v6, v6, v4
	v_add_f32_e32 v8, v5, v6
	v_mul_f32_e32 v9, v8, v8
	v_fmamk_f32 v4, v9, 0x3e9b6dac, v233
	v_fmaak_f32 v217, v9, v4, 0x3f2aaada
	v_cvt_f32_i32_e32 v4, v36
	v_sub_f32_e32 v5, v8, v5
	v_sub_f32_e32 v5, v6, v5
	v_ldexp_f32 v34, v5, 1
	v_mul_f32_e32 v5, v8, v9
	v_ldexp_f32 v7, v8, 1
	v_pk_mul_f32 v[8:9], v[4:5], v[216:217]
	s_nop 0
	v_fma_f32 v6, v4, s81, -v8
	v_fmac_f32_e32 v6, 0xb102e308, v4
	v_pk_add_f32 v[4:5], v[8:9], v[6:7]
	s_nop 0
	v_sub_f32_e32 v7, v5, v7
	v_sub_f32_e32 v7, v9, v7
	v_add_f32_e32 v35, v34, v7
	v_mov_b32_e32 v34, v8
	v_pk_add_f32 v[8:9], v[4:5], v[8:9] neg_lo:[0,1] neg_hi:[0,1]
	v_pk_add_f32 v[36:37], v[4:5], v[34:35]
	v_mov_b32_e32 v7, v4
	v_mov_b32_e32 v9, v37
	v_pk_add_f32 v[38:39], v[6:7], v[8:9] neg_lo:[0,1] neg_hi:[0,1]
	v_pk_add_f32 v[6:7], v[6:7], v[8:9]
	v_mov_b32_e32 v34, v35
	v_pk_add_f32 v[8:9], v[6:7], v[4:5] op_sel:[1,0] op_sel_hi:[0,1] neg_lo:[0,1] neg_hi:[0,1]
	v_pk_add_f32 v[40:41], v[36:37], v[8:9] op_sel_hi:[1,0] neg_lo:[0,1] neg_hi:[0,1]
	v_mov_b32_e32 v36, v37
	v_mov_b32_e32 v37, v7
	v_pk_mov_b32 v[8:9], v[4:5], v[8:9] op_sel:[1,0]
	v_mov_b32_e32 v35, v4
	v_pk_add_f32 v[8:9], v[36:37], v[8:9] neg_lo:[0,1] neg_hi:[0,1]
	v_mov_b32_e32 v40, v38
	v_pk_add_f32 v[4:5], v[34:35], v[8:9] neg_lo:[0,1] neg_hi:[0,1]
	v_mov_b32_e32 v39, v7
	v_pk_add_f32 v[8:9], v[40:41], v[4:5]
	s_nop 0
	v_pk_add_f32 v[34:35], v[8:9], v[8:9] op_sel:[0,1] op_sel_hi:[1,0]
	s_nop 0
	v_pk_add_f32 v[6:7], v[6:7], v[34:35] op_sel:[1,0] op_sel_hi:[0,1]
	v_mov_b32_e32 v9, v6
	v_pk_add_f32 v[36:37], v[8:9], v[38:39] neg_lo:[0,1] neg_hi:[0,1]
	v_mov_b32_e32 v5, v34
	v_sub_f32_e32 v7, v8, v36
	v_pk_add_f32 v[4:5], v[4:5], v[36:37] neg_lo:[0,1] neg_hi:[0,1]
	v_sub_f32_e32 v7, v38, v7
	v_add_f32_e32 v4, v4, v7
	v_add_f32_e32 v4, v4, v5
	v_add_f32_e32 v4, v6, v4
	v_cndmask_b32_e64 v4, v239, v4, s[22:23]
	v_cmp_ngt_f32_e64 s[22:23], -1.0, v3
	s_nop 1
	v_cndmask_b32_e64 v4, v218, v4, s[22:23]
	v_cmp_neq_f32_e64 s[22:23], -1.0, v3
	s_nop 1
	v_cndmask_b32_e64 v4, v238, v4, s[22:23]
	v_cmp_lt_f32_e64 s[22:23], |v3|, s83
	s_nop 1
	v_cndmask_b32_e64 v3, v4, v3, s[22:23]
	v_sub_f32_e32 v2, v2, v3
	ds_write_b32 v33, v2 offset:32
	s_branch .LBB0_491
